# GEMM_IN: each XCD walks the rounds of output tiles in a rotated order so XCDs do not stream the same weight panels at the same time
# speedup vs baseline: 1.0092x; 1.0092x over previous
.LBB0_271:
	v_and_b32_e32 v150, 63, v128
	v_lshrrev_b32_e32 v151, 6, v128
	v_lshrrev_b32_e32 v152, 3, v150
	v_readfirstlane_b32 s0, v151
	v_and_b32_e32 v153, 7, v150
	v_xor_b32_e32 v153, v153, v152
	v_lshlrev_b32_e32 v153, 4, v153
	v_lshl_add_u32 v153, v152, 11, v153
	s_lshl_b32 s1, s0, 16
	v_add_u32_e32 v132, s1, v153
	v_add_u32_e32 v133, 0x3c00, v132
	v_add_u32_e32 v134, 0x7800, v132
	v_add_u32_e32 v135, 0xb400, v132
	s_lshl_b32 s1, s0, 12
	s_add_u32 s5, s1, 0
	s_add_u32 s6, s1, 16384
	s_add_u32 s7, s1, 45056
	s_add_u32 s8, s1, 61440
	v_and_b32_e32 v152, 15, v150
	v_lshrrev_b32_e32 v153, 4, v150
	v_and_b32_e32 v154, 7, v152
	v_xor_b32_e32 v154, v154, v153
	v_lshlrev_b32_e32 v154, 4, v154
	v_lshl_add_u32 v154, v152, 7, v154
	s_lshr_b32 s1, s0, 1
	s_lshl_b32 s1, s1, 13
	v_add_u32_e32 v136, s1, v154
	v_xor_b32_e32 v137, 64, v136
	v_add_u32_e32 v138, 0xb000, v136
	v_add_u32_e32 v139, 0xb000, v137
	s_and_b32 s1, s0, 1
	s_lshl_b32 s1, s1, 13
	s_add_u32 s1, s1, 16384
	v_add_u32_e32 v140, s1, v154
	v_xor_b32_e32 v141, 64, v140
	v_add_u32_e32 v142, 0xb000, v140
	v_add_u32_e32 v143, 0xb000, v141
	s_and_b32 s1, s0, 1
	s_lshl_b32 s1, s1, 6
	v_add_u32_e32 v152, s1, v152
	v_mov_b32_e32 v154, 0x4a00
	v_mul_lo_u32 v152, v152, v154
	v_lshlrev_b32_e32 v153, 3, v153
	s_lshr_b32 s1, s0, 1
	s_lshl_b32 s1, s1, 7
	v_add3_u32 v146, v152, v153, s1
	v_add_u32_e32 v147, 0x4a000, v146
	v_add_u32_e32 v148, 0x94000, v146
	v_add_u32_e32 v149, 0xde000, v146
	v_readlane_b32 s25, v252, 0
	s_mov_b32 s101, s25
	s_mov_b32 s100, 0
	s_and_b32 s0, s25, 7
	s_lshl_b32 s0, s0, 9
	s_add_i32 s25, s25, s0
	v_readlane_b32 s98, v252, 0
	s_and_b32 s99, s98, 7
	s_lshr_b32 s98, s98, 3
	s_lshl_b32 s99, s99, 1
	s_add_i32 s98, s98, s99
	s_and_b32 s98, s98, 15
	s_and_b32 s0, s25, 63
	s_lshr_b32 s1, s25, 6
	s_mul_i32 s4, s70, 0x1280000
	s_lshl_b32 s39, s1, 18
	s_add_u32 s4, s4, s39
	s_add_u32 s26, s96, s4
	s_addc_u32 s27, s97, 0
	s_lshl_b32 s4, s0, 18
	s_add_u32 s4, s4, 0x82a6100
	s_add_u32 s28, s96, s4
	s_addc_u32 s29, s97, 0
	s_lshl_b32 s0, s98, 7
	s_add_u32 s26, s26, s0
	s_addc_u32 s27, s27, 0
	s_add_u32 s28, s28, s0
	s_addc_u32 s29, s29, 0
	s_mov_b32 s99, s98
	s_mov_b32 m0, s5
	s_nop 0
	global_load_lds_dwordx4 v132, s[26:27] offset:0
	global_load_lds_dwordx4 v133, s[26:27] offset:1024
	global_load_lds_dwordx4 v134, s[26:27] offset:2048
	global_load_lds_dwordx4 v135, s[26:27] offset:3072
	s_mov_b32 m0, s6
	s_nop 0
	global_load_lds_dwordx4 v132, s[28:29] offset:0
	global_load_lds_dwordx4 v133, s[28:29] offset:1024
	global_load_lds_dwordx4 v134, s[28:29] offset:2048
	global_load_lds_dwordx4 v135, s[28:29] offset:3072
	s_waitcnt vmcnt(0)
.Lgin_tile:
	s_waitcnt vmcnt(16)
	s_barrier
	s_add_i32 s99, s99, 1
	s_cmp_eq_u32 s99, 16
	s_movk_i32 s0, 0x80
	s_cselect_b32 s0, 0xfffff880, s0
	s_cselect_b32 s99, 0, s99
	s_ashr_i32 s1, s0, 31
	s_add_u32 s26, s26, s0
	s_addc_u32 s27, s27, s1
	s_add_u32 s28, s28, s0
	s_addc_u32 s29, s29, s1
	s_mov_b32 m0, s7
	s_nop 0
	global_load_lds_dwordx4 v132, s[26:27] offset:0
	global_load_lds_dwordx4 v133, s[26:27] offset:1024
	global_load_lds_dwordx4 v134, s[26:27] offset:2048
	global_load_lds_dwordx4 v135, s[26:27] offset:3072
	s_mov_b32 m0, s8
	s_nop 0
	global_load_lds_dwordx4 v132, s[28:29] offset:0
	global_load_lds_dwordx4 v133, s[28:29] offset:1024
	global_load_lds_dwordx4 v134, s[28:29] offset:2048
	global_load_lds_dwordx4 v135, s[28:29] offset:3072
	ds_read_b128 v[64:67], v136 offset:0
	ds_read_b128 v[96:99], v140 offset:0
	ds_read_b128 v[100:103], v140 offset:2048
	ds_read_b128 v[104:107], v140 offset:4096
	ds_read_b128 v[108:111], v140 offset:6144
	ds_read_b128 v[68:71], v136 offset:2048
	ds_read_b128 v[72:75], v136 offset:4096
	ds_read_b128 v[76:79], v136 offset:6144
	s_waitcnt lgkmcnt(3)
	v_mfma_f32_16x16x32_bf16 v[0:3], v[64:67], v[96:99], 0
	v_mfma_f32_16x16x32_bf16 v[4:7], v[64:67], v[100:103], 0
	ds_read_b128 v[80:83], v137 offset:0
	v_mfma_f32_16x16x32_bf16 v[8:11], v[64:67], v[104:107], 0
	v_mfma_f32_16x16x32_bf16 v[12:15], v[64:67], v[108:111], 0
	ds_read_b128 v[112:115], v141 offset:0
	s_waitcnt lgkmcnt(4)
	v_mfma_f32_16x16x32_bf16 v[16:19], v[68:71], v[96:99], 0
	v_mfma_f32_16x16x32_bf16 v[20:23], v[68:71], v[100:103], 0
	ds_read_b128 v[116:119], v141 offset:2048
	v_mfma_f32_16x16x32_bf16 v[24:27], v[68:71], v[104:107], 0
	v_mfma_f32_16x16x32_bf16 v[28:31], v[68:71], v[108:111], 0
	ds_read_b128 v[120:123], v141 offset:4096
	s_waitcnt lgkmcnt(5)
	v_mfma_f32_16x16x32_bf16 v[32:35], v[72:75], v[96:99], 0
	v_mfma_f32_16x16x32_bf16 v[36:39], v[72:75], v[100:103], 0
	ds_read_b128 v[124:127], v141 offset:6144
	v_mfma_f32_16x16x32_bf16 v[40:43], v[72:75], v[104:107], 0
	v_mfma_f32_16x16x32_bf16 v[44:47], v[72:75], v[108:111], 0
	ds_read_b128 v[84:87], v137 offset:2048
	s_waitcnt lgkmcnt(6)
	v_mfma_f32_16x16x32_bf16 v[48:51], v[76:79], v[96:99], 0
	v_mfma_f32_16x16x32_bf16 v[52:55], v[76:79], v[100:103], 0
	ds_read_b128 v[88:91], v137 offset:4096
	v_mfma_f32_16x16x32_bf16 v[56:59], v[76:79], v[104:107], 0
	v_mfma_f32_16x16x32_bf16 v[60:63], v[76:79], v[108:111], 0
	ds_read_b128 v[92:95], v137 offset:6144
	s_waitcnt lgkmcnt(3)
	v_mfma_f32_16x16x32_bf16 v[0:3], v[80:83], v[112:115], v[0:3]
	v_mfma_f32_16x16x32_bf16 v[4:7], v[80:83], v[116:119], v[4:7]
	v_mfma_f32_16x16x32_bf16 v[8:11], v[80:83], v[120:123], v[8:11]
	v_mfma_f32_16x16x32_bf16 v[12:15], v[80:83], v[124:127], v[12:15]
	s_waitcnt lgkmcnt(2)
	v_mfma_f32_16x16x32_bf16 v[16:19], v[84:87], v[112:115], v[16:19]
	v_mfma_f32_16x16x32_bf16 v[20:23], v[84:87], v[116:119], v[20:23]
	v_mfma_f32_16x16x32_bf16 v[24:27], v[84:87], v[120:123], v[24:27]
	v_mfma_f32_16x16x32_bf16 v[28:31], v[84:87], v[124:127], v[28:31]
	s_waitcnt lgkmcnt(1)
	v_mfma_f32_16x16x32_bf16 v[32:35], v[88:91], v[112:115], v[32:35]
	v_mfma_f32_16x16x32_bf16 v[36:39], v[88:91], v[116:119], v[36:39]
	v_mfma_f32_16x16x32_bf16 v[40:43], v[88:91], v[120:123], v[40:43]
	v_mfma_f32_16x16x32_bf16 v[44:47], v[88:91], v[124:127], v[44:47]
	s_waitcnt lgkmcnt(0)
	v_mfma_f32_16x16x32_bf16 v[48:51], v[92:95], v[112:115], v[48:51]
	v_mfma_f32_16x16x32_bf16 v[52:55], v[92:95], v[116:119], v[52:55]
	v_mfma_f32_16x16x32_bf16 v[56:59], v[92:95], v[120:123], v[56:59]
	v_mfma_f32_16x16x32_bf16 v[60:63], v[92:95], v[124:127], v[60:63]
	s_waitcnt vmcnt(0)
	s_barrier
	s_add_i32 s99, s99, 1
	s_cmp_eq_u32 s99, 16
	s_movk_i32 s0, 0x80
	s_cselect_b32 s0, 0xfffff880, s0
	s_cselect_b32 s99, 0, s99
	s_ashr_i32 s1, s0, 31
	s_add_u32 s26, s26, s0
	s_addc_u32 s27, s27, s1
	s_add_u32 s28, s28, s0
	s_addc_u32 s29, s29, s1
	s_mov_b32 m0, s5
	s_nop 0
	global_load_lds_dwordx4 v132, s[26:27] offset:0
	global_load_lds_dwordx4 v133, s[26:27] offset:1024
	global_load_lds_dwordx4 v134, s[26:27] offset:2048
	global_load_lds_dwordx4 v135, s[26:27] offset:3072
	s_mov_b32 m0, s6
	s_nop 0
	global_load_lds_dwordx4 v132, s[28:29] offset:0
	global_load_lds_dwordx4 v133, s[28:29] offset:1024
	global_load_lds_dwordx4 v134, s[28:29] offset:2048
	global_load_lds_dwordx4 v135, s[28:29] offset:3072
	ds_read_b128 v[64:67], v138 offset:0
	ds_read_b128 v[96:99], v142 offset:0
	ds_read_b128 v[100:103], v142 offset:2048
	ds_read_b128 v[104:107], v142 offset:4096
	ds_read_b128 v[108:111], v142 offset:6144
	ds_read_b128 v[68:71], v138 offset:2048
	ds_read_b128 v[72:75], v138 offset:4096
	ds_read_b128 v[76:79], v138 offset:6144
	s_waitcnt lgkmcnt(3)
	v_mfma_f32_16x16x32_bf16 v[0:3], v[64:67], v[96:99], v[0:3]
	v_mfma_f32_16x16x32_bf16 v[4:7], v[64:67], v[100:103], v[4:7]
	ds_read_b128 v[80:83], v139 offset:0
	v_mfma_f32_16x16x32_bf16 v[8:11], v[64:67], v[104:107], v[8:11]
	v_mfma_f32_16x16x32_bf16 v[12:15], v[64:67], v[108:111], v[12:15]
	ds_read_b128 v[112:115], v143 offset:0
	s_waitcnt lgkmcnt(4)
	v_mfma_f32_16x16x32_bf16 v[16:19], v[68:71], v[96:99], v[16:19]
	v_mfma_f32_16x16x32_bf16 v[20:23], v[68:71], v[100:103], v[20:23]
	ds_read_b128 v[116:119], v143 offset:2048
	v_mfma_f32_16x16x32_bf16 v[24:27], v[68:71], v[104:107], v[24:27]
	v_mfma_f32_16x16x32_bf16 v[28:31], v[68:71], v[108:111], v[28:31]
	ds_read_b128 v[120:123], v143 offset:4096
	s_waitcnt lgkmcnt(5)
	v_mfma_f32_16x16x32_bf16 v[32:35], v[72:75], v[96:99], v[32:35]
	v_mfma_f32_16x16x32_bf16 v[36:39], v[72:75], v[100:103], v[36:39]
	ds_read_b128 v[124:127], v143 offset:6144
	v_mfma_f32_16x16x32_bf16 v[40:43], v[72:75], v[104:107], v[40:43]
	v_mfma_f32_16x16x32_bf16 v[44:47], v[72:75], v[108:111], v[44:47]
	ds_read_b128 v[84:87], v139 offset:2048
	s_waitcnt lgkmcnt(6)
	v_mfma_f32_16x16x32_bf16 v[48:51], v[76:79], v[96:99], v[48:51]
	v_mfma_f32_16x16x32_bf16 v[52:55], v[76:79], v[100:103], v[52:55]
	ds_read_b128 v[88:91], v139 offset:4096
	v_mfma_f32_16x16x32_bf16 v[56:59], v[76:79], v[104:107], v[56:59]
	v_mfma_f32_16x16x32_bf16 v[60:63], v[76:79], v[108:111], v[60:63]
	ds_read_b128 v[92:95], v139 offset:6144
	s_waitcnt lgkmcnt(3)
	v_mfma_f32_16x16x32_bf16 v[0:3], v[80:83], v[112:115], v[0:3]
	v_mfma_f32_16x16x32_bf16 v[4:7], v[80:83], v[116:119], v[4:7]
	v_mfma_f32_16x16x32_bf16 v[8:11], v[80:83], v[120:123], v[8:11]
	v_mfma_f32_16x16x32_bf16 v[12:15], v[80:83], v[124:127], v[12:15]
	s_waitcnt lgkmcnt(2)
	v_mfma_f32_16x16x32_bf16 v[16:19], v[84:87], v[112:115], v[16:19]
	v_mfma_f32_16x16x32_bf16 v[20:23], v[84:87], v[116:119], v[20:23]
	v_mfma_f32_16x16x32_bf16 v[24:27], v[84:87], v[120:123], v[24:27]
	v_mfma_f32_16x16x32_bf16 v[28:31], v[84:87], v[124:127], v[28:31]
	s_waitcnt lgkmcnt(1)
	v_mfma_f32_16x16x32_bf16 v[32:35], v[88:91], v[112:115], v[32:35]
	v_mfma_f32_16x16x32_bf16 v[36:39], v[88:91], v[116:119], v[36:39]
	v_mfma_f32_16x16x32_bf16 v[40:43], v[88:91], v[120:123], v[40:43]
	v_mfma_f32_16x16x32_bf16 v[44:47], v[88:91], v[124:127], v[44:47]
	s_waitcnt lgkmcnt(0)
	v_mfma_f32_16x16x32_bf16 v[48:51], v[92:95], v[112:115], v[48:51]
	v_mfma_f32_16x16x32_bf16 v[52:55], v[92:95], v[116:119], v[52:55]
	v_mfma_f32_16x16x32_bf16 v[56:59], v[92:95], v[120:123], v[56:59]
	v_mfma_f32_16x16x32_bf16 v[60:63], v[92:95], v[124:127], v[60:63]
	s_waitcnt vmcnt(0)
	s_barrier
	s_add_i32 s99, s99, 1
	s_cmp_eq_u32 s99, 16
	s_movk_i32 s0, 0x80
	s_cselect_b32 s0, 0xfffff880, s0
	s_cselect_b32 s99, 0, s99
	s_ashr_i32 s1, s0, 31
	s_add_u32 s26, s26, s0
	s_addc_u32 s27, s27, s1
	s_add_u32 s28, s28, s0
	s_addc_u32 s29, s29, s1
	s_mov_b32 m0, s7
	s_nop 0
	global_load_lds_dwordx4 v132, s[26:27] offset:0
	global_load_lds_dwordx4 v133, s[26:27] offset:1024
	global_load_lds_dwordx4 v134, s[26:27] offset:2048
	global_load_lds_dwordx4 v135, s[26:27] offset:3072
	s_mov_b32 m0, s8
	s_nop 0
	global_load_lds_dwordx4 v132, s[28:29] offset:0
	global_load_lds_dwordx4 v133, s[28:29] offset:1024
	global_load_lds_dwordx4 v134, s[28:29] offset:2048
	global_load_lds_dwordx4 v135, s[28:29] offset:3072
	ds_read_b128 v[64:67], v136 offset:0
	ds_read_b128 v[96:99], v140 offset:0
	ds_read_b128 v[100:103], v140 offset:2048
	ds_read_b128 v[104:107], v140 offset:4096
	ds_read_b128 v[108:111], v140 offset:6144
	ds_read_b128 v[68:71], v136 offset:2048
	ds_read_b128 v[72:75], v136 offset:4096
	ds_read_b128 v[76:79], v136 offset:6144
	s_waitcnt lgkmcnt(3)
	v_mfma_f32_16x16x32_bf16 v[0:3], v[64:67], v[96:99], v[0:3]
	v_mfma_f32_16x16x32_bf16 v[4:7], v[64:67], v[100:103], v[4:7]
	ds_read_b128 v[80:83], v137 offset:0
	v_mfma_f32_16x16x32_bf16 v[8:11], v[64:67], v[104:107], v[8:11]
	v_mfma_f32_16x16x32_bf16 v[12:15], v[64:67], v[108:111], v[12:15]
	ds_read_b128 v[112:115], v141 offset:0
	s_waitcnt lgkmcnt(4)
	v_mfma_f32_16x16x32_bf16 v[16:19], v[68:71], v[96:99], v[16:19]
	v_mfma_f32_16x16x32_bf16 v[20:23], v[68:71], v[100:103], v[20:23]
	ds_read_b128 v[116:119], v141 offset:2048
	v_mfma_f32_16x16x32_bf16 v[24:27], v[68:71], v[104:107], v[24:27]
	v_mfma_f32_16x16x32_bf16 v[28:31], v[68:71], v[108:111], v[28:31]
	ds_read_b128 v[120:123], v141 offset:4096
	s_waitcnt lgkmcnt(5)
	v_mfma_f32_16x16x32_bf16 v[32:35], v[72:75], v[96:99], v[32:35]
	v_mfma_f32_16x16x32_bf16 v[36:39], v[72:75], v[100:103], v[36:39]
	ds_read_b128 v[124:127], v141 offset:6144
	v_mfma_f32_16x16x32_bf16 v[40:43], v[72:75], v[104:107], v[40:43]
	v_mfma_f32_16x16x32_bf16 v[44:47], v[72:75], v[108:111], v[44:47]
	ds_read_b128 v[84:87], v137 offset:2048
	s_waitcnt lgkmcnt(6)
	v_mfma_f32_16x16x32_bf16 v[48:51], v[76:79], v[96:99], v[48:51]
	v_mfma_f32_16x16x32_bf16 v[52:55], v[76:79], v[100:103], v[52:55]
	ds_read_b128 v[88:91], v137 offset:4096
	v_mfma_f32_16x16x32_bf16 v[56:59], v[76:79], v[104:107], v[56:59]
	v_mfma_f32_16x16x32_bf16 v[60:63], v[76:79], v[108:111], v[60:63]
	ds_read_b128 v[92:95], v137 offset:6144
	s_waitcnt lgkmcnt(3)
	v_mfma_f32_16x16x32_bf16 v[0:3], v[80:83], v[112:115], v[0:3]
	v_mfma_f32_16x16x32_bf16 v[4:7], v[80:83], v[116:119], v[4:7]
	v_mfma_f32_16x16x32_bf16 v[8:11], v[80:83], v[120:123], v[8:11]
	v_mfma_f32_16x16x32_bf16 v[12:15], v[80:83], v[124:127], v[12:15]
	s_waitcnt lgkmcnt(2)
	v_mfma_f32_16x16x32_bf16 v[16:19], v[84:87], v[112:115], v[16:19]
	v_mfma_f32_16x16x32_bf16 v[20:23], v[84:87], v[116:119], v[20:23]
	v_mfma_f32_16x16x32_bf16 v[24:27], v[84:87], v[120:123], v[24:27]
	v_mfma_f32_16x16x32_bf16 v[28:31], v[84:87], v[124:127], v[28:31]
	s_waitcnt lgkmcnt(1)
	v_mfma_f32_16x16x32_bf16 v[32:35], v[88:91], v[112:115], v[32:35]
	v_mfma_f32_16x16x32_bf16 v[36:39], v[88:91], v[116:119], v[36:39]
	v_mfma_f32_16x16x32_bf16 v[40:43], v[88:91], v[120:123], v[40:43]
	v_mfma_f32_16x16x32_bf16 v[44:47], v[88:91], v[124:127], v[44:47]
	s_waitcnt lgkmcnt(0)
	v_mfma_f32_16x16x32_bf16 v[48:51], v[92:95], v[112:115], v[48:51]
	v_mfma_f32_16x16x32_bf16 v[52:55], v[92:95], v[116:119], v[52:55]
	v_mfma_f32_16x16x32_bf16 v[56:59], v[92:95], v[120:123], v[56:59]
	v_mfma_f32_16x16x32_bf16 v[60:63], v[92:95], v[124:127], v[60:63]
	s_waitcnt vmcnt(0)
	s_barrier
	s_add_i32 s99, s99, 1
	s_cmp_eq_u32 s99, 16
	s_movk_i32 s0, 0x80
	s_cselect_b32 s0, 0xfffff880, s0
	s_cselect_b32 s99, 0, s99
	s_ashr_i32 s1, s0, 31
	s_add_u32 s26, s26, s0
	s_addc_u32 s27, s27, s1
	s_add_u32 s28, s28, s0
	s_addc_u32 s29, s29, s1
	s_mov_b32 m0, s5
	s_nop 0
	global_load_lds_dwordx4 v132, s[26:27] offset:0
	global_load_lds_dwordx4 v133, s[26:27] offset:1024
	global_load_lds_dwordx4 v134, s[26:27] offset:2048
	global_load_lds_dwordx4 v135, s[26:27] offset:3072
	s_mov_b32 m0, s6
	s_nop 0
	global_load_lds_dwordx4 v132, s[28:29] offset:0
	global_load_lds_dwordx4 v133, s[28:29] offset:1024
	global_load_lds_dwordx4 v134, s[28:29] offset:2048
	global_load_lds_dwordx4 v135, s[28:29] offset:3072
	ds_read_b128 v[64:67], v138 offset:0
	ds_read_b128 v[96:99], v142 offset:0
	ds_read_b128 v[100:103], v142 offset:2048
	ds_read_b128 v[104:107], v142 offset:4096
	ds_read_b128 v[108:111], v142 offset:6144
	ds_read_b128 v[68:71], v138 offset:2048
	ds_read_b128 v[72:75], v138 offset:4096
	ds_read_b128 v[76:79], v138 offset:6144
	s_waitcnt lgkmcnt(3)
	v_mfma_f32_16x16x32_bf16 v[0:3], v[64:67], v[96:99], v[0:3]
	v_mfma_f32_16x16x32_bf16 v[4:7], v[64:67], v[100:103], v[4:7]
	ds_read_b128 v[80:83], v139 offset:0
	v_mfma_f32_16x16x32_bf16 v[8:11], v[64:67], v[104:107], v[8:11]
	v_mfma_f32_16x16x32_bf16 v[12:15], v[64:67], v[108:111], v[12:15]
	ds_read_b128 v[112:115], v143 offset:0
	s_waitcnt lgkmcnt(4)
	v_mfma_f32_16x16x32_bf16 v[16:19], v[68:71], v[96:99], v[16:19]
	v_mfma_f32_16x16x32_bf16 v[20:23], v[68:71], v[100:103], v[20:23]
	ds_read_b128 v[116:119], v143 offset:2048
	v_mfma_f32_16x16x32_bf16 v[24:27], v[68:71], v[104:107], v[24:27]
	v_mfma_f32_16x16x32_bf16 v[28:31], v[68:71], v[108:111], v[28:31]
	ds_read_b128 v[120:123], v143 offset:4096
	s_waitcnt lgkmcnt(5)
	v_mfma_f32_16x16x32_bf16 v[32:35], v[72:75], v[96:99], v[32:35]
	v_mfma_f32_16x16x32_bf16 v[36:39], v[72:75], v[100:103], v[36:39]
	ds_read_b128 v[124:127], v143 offset:6144
	v_mfma_f32_16x16x32_bf16 v[40:43], v[72:75], v[104:107], v[40:43]
	v_mfma_f32_16x16x32_bf16 v[44:47], v[72:75], v[108:111], v[44:47]
	ds_read_b128 v[84:87], v139 offset:2048
	s_waitcnt lgkmcnt(6)
	v_mfma_f32_16x16x32_bf16 v[48:51], v[76:79], v[96:99], v[48:51]
	v_mfma_f32_16x16x32_bf16 v[52:55], v[76:79], v[100:103], v[52:55]
	ds_read_b128 v[88:91], v139 offset:4096
	v_mfma_f32_16x16x32_bf16 v[56:59], v[76:79], v[104:107], v[56:59]
	v_mfma_f32_16x16x32_bf16 v[60:63], v[76:79], v[108:111], v[60:63]
	ds_read_b128 v[92:95], v139 offset:6144
	s_waitcnt lgkmcnt(3)
	v_mfma_f32_16x16x32_bf16 v[0:3], v[80:83], v[112:115], v[0:3]
	v_mfma_f32_16x16x32_bf16 v[4:7], v[80:83], v[116:119], v[4:7]
	v_mfma_f32_16x16x32_bf16 v[8:11], v[80:83], v[120:123], v[8:11]
	v_mfma_f32_16x16x32_bf16 v[12:15], v[80:83], v[124:127], v[12:15]
	s_waitcnt lgkmcnt(2)
	v_mfma_f32_16x16x32_bf16 v[16:19], v[84:87], v[112:115], v[16:19]
	v_mfma_f32_16x16x32_bf16 v[20:23], v[84:87], v[116:119], v[20:23]
	v_mfma_f32_16x16x32_bf16 v[24:27], v[84:87], v[120:123], v[24:27]
	v_mfma_f32_16x16x32_bf16 v[28:31], v[84:87], v[124:127], v[28:31]
	s_waitcnt lgkmcnt(1)
	v_mfma_f32_16x16x32_bf16 v[32:35], v[88:91], v[112:115], v[32:35]
	v_mfma_f32_16x16x32_bf16 v[36:39], v[88:91], v[116:119], v[36:39]
	v_mfma_f32_16x16x32_bf16 v[40:43], v[88:91], v[120:123], v[40:43]
	v_mfma_f32_16x16x32_bf16 v[44:47], v[88:91], v[124:127], v[44:47]
	s_waitcnt lgkmcnt(0)
	v_mfma_f32_16x16x32_bf16 v[48:51], v[92:95], v[112:115], v[48:51]
	v_mfma_f32_16x16x32_bf16 v[52:55], v[92:95], v[116:119], v[52:55]
	v_mfma_f32_16x16x32_bf16 v[56:59], v[92:95], v[120:123], v[56:59]
	v_mfma_f32_16x16x32_bf16 v[60:63], v[92:95], v[124:127], v[60:63]
	s_waitcnt vmcnt(0)
	s_barrier
	s_add_i32 s99, s99, 1
	s_cmp_eq_u32 s99, 16
	s_movk_i32 s0, 0x80
	s_cselect_b32 s0, 0xfffff880, s0
	s_cselect_b32 s99, 0, s99
	s_ashr_i32 s1, s0, 31
	s_add_u32 s26, s26, s0
	s_addc_u32 s27, s27, s1
	s_add_u32 s28, s28, s0
	s_addc_u32 s29, s29, s1
	s_mov_b32 m0, s7
	s_nop 0
	global_load_lds_dwordx4 v132, s[26:27] offset:0
	global_load_lds_dwordx4 v133, s[26:27] offset:1024
	global_load_lds_dwordx4 v134, s[26:27] offset:2048
	global_load_lds_dwordx4 v135, s[26:27] offset:3072
	s_mov_b32 m0, s8
	s_nop 0
	global_load_lds_dwordx4 v132, s[28:29] offset:0
	global_load_lds_dwordx4 v133, s[28:29] offset:1024
	global_load_lds_dwordx4 v134, s[28:29] offset:2048
	global_load_lds_dwordx4 v135, s[28:29] offset:3072
	ds_read_b128 v[64:67], v136 offset:0
	ds_read_b128 v[96:99], v140 offset:0
	ds_read_b128 v[100:103], v140 offset:2048
	ds_read_b128 v[104:107], v140 offset:4096
	ds_read_b128 v[108:111], v140 offset:6144
	ds_read_b128 v[68:71], v136 offset:2048
	ds_read_b128 v[72:75], v136 offset:4096
	ds_read_b128 v[76:79], v136 offset:6144
	s_waitcnt lgkmcnt(3)
	v_mfma_f32_16x16x32_bf16 v[0:3], v[64:67], v[96:99], v[0:3]
	v_mfma_f32_16x16x32_bf16 v[4:7], v[64:67], v[100:103], v[4:7]
	ds_read_b128 v[80:83], v137 offset:0
	v_mfma_f32_16x16x32_bf16 v[8:11], v[64:67], v[104:107], v[8:11]
	v_mfma_f32_16x16x32_bf16 v[12:15], v[64:67], v[108:111], v[12:15]
	ds_read_b128 v[112:115], v141 offset:0
	s_waitcnt lgkmcnt(4)
	v_mfma_f32_16x16x32_bf16 v[16:19], v[68:71], v[96:99], v[16:19]
	v_mfma_f32_16x16x32_bf16 v[20:23], v[68:71], v[100:103], v[20:23]
	ds_read_b128 v[116:119], v141 offset:2048
	v_mfma_f32_16x16x32_bf16 v[24:27], v[68:71], v[104:107], v[24:27]
	v_mfma_f32_16x16x32_bf16 v[28:31], v[68:71], v[108:111], v[28:31]
	ds_read_b128 v[120:123], v141 offset:4096
	s_waitcnt lgkmcnt(5)
	v_mfma_f32_16x16x32_bf16 v[32:35], v[72:75], v[96:99], v[32:35]
	v_mfma_f32_16x16x32_bf16 v[36:39], v[72:75], v[100:103], v[36:39]
	ds_read_b128 v[124:127], v141 offset:6144
	v_mfma_f32_16x16x32_bf16 v[40:43], v[72:75], v[104:107], v[40:43]
	v_mfma_f32_16x16x32_bf16 v[44:47], v[72:75], v[108:111], v[44:47]
	ds_read_b128 v[84:87], v137 offset:2048
	s_waitcnt lgkmcnt(6)
	v_mfma_f32_16x16x32_bf16 v[48:51], v[76:79], v[96:99], v[48:51]
	v_mfma_f32_16x16x32_bf16 v[52:55], v[76:79], v[100:103], v[52:55]
	ds_read_b128 v[88:91], v137 offset:4096
	v_mfma_f32_16x16x32_bf16 v[56:59], v[76:79], v[104:107], v[56:59]
	v_mfma_f32_16x16x32_bf16 v[60:63], v[76:79], v[108:111], v[60:63]
	ds_read_b128 v[92:95], v137 offset:6144
	s_waitcnt lgkmcnt(3)
	v_mfma_f32_16x16x32_bf16 v[0:3], v[80:83], v[112:115], v[0:3]
	v_mfma_f32_16x16x32_bf16 v[4:7], v[80:83], v[116:119], v[4:7]
	v_mfma_f32_16x16x32_bf16 v[8:11], v[80:83], v[120:123], v[8:11]
	v_mfma_f32_16x16x32_bf16 v[12:15], v[80:83], v[124:127], v[12:15]
	s_waitcnt lgkmcnt(2)
	v_mfma_f32_16x16x32_bf16 v[16:19], v[84:87], v[112:115], v[16:19]
	v_mfma_f32_16x16x32_bf16 v[20:23], v[84:87], v[116:119], v[20:23]
	v_mfma_f32_16x16x32_bf16 v[24:27], v[84:87], v[120:123], v[24:27]
	v_mfma_f32_16x16x32_bf16 v[28:31], v[84:87], v[124:127], v[28:31]
	s_waitcnt lgkmcnt(1)
	v_mfma_f32_16x16x32_bf16 v[32:35], v[88:91], v[112:115], v[32:35]
	v_mfma_f32_16x16x32_bf16 v[36:39], v[88:91], v[116:119], v[36:39]
	v_mfma_f32_16x16x32_bf16 v[40:43], v[88:91], v[120:123], v[40:43]
	v_mfma_f32_16x16x32_bf16 v[44:47], v[88:91], v[124:127], v[44:47]
	s_waitcnt lgkmcnt(0)
	v_mfma_f32_16x16x32_bf16 v[48:51], v[92:95], v[112:115], v[48:51]
	v_mfma_f32_16x16x32_bf16 v[52:55], v[92:95], v[116:119], v[52:55]
	v_mfma_f32_16x16x32_bf16 v[56:59], v[92:95], v[120:123], v[56:59]
	v_mfma_f32_16x16x32_bf16 v[60:63], v[92:95], v[124:127], v[60:63]
	s_waitcnt vmcnt(0)
	s_barrier
	s_add_i32 s99, s99, 1
	s_cmp_eq_u32 s99, 16
	s_movk_i32 s0, 0x80
	s_cselect_b32 s0, 0xfffff880, s0
	s_cselect_b32 s99, 0, s99
	s_ashr_i32 s1, s0, 31
	s_add_u32 s26, s26, s0
	s_addc_u32 s27, s27, s1
	s_add_u32 s28, s28, s0
	s_addc_u32 s29, s29, s1
	s_mov_b32 m0, s5
	s_nop 0
	global_load_lds_dwordx4 v132, s[26:27] offset:0
	global_load_lds_dwordx4 v133, s[26:27] offset:1024
	global_load_lds_dwordx4 v134, s[26:27] offset:2048
	global_load_lds_dwordx4 v135, s[26:27] offset:3072
	s_mov_b32 m0, s6
	s_nop 0
	global_load_lds_dwordx4 v132, s[28:29] offset:0
	global_load_lds_dwordx4 v133, s[28:29] offset:1024
	global_load_lds_dwordx4 v134, s[28:29] offset:2048
	global_load_lds_dwordx4 v135, s[28:29] offset:3072
	ds_read_b128 v[64:67], v138 offset:0
	ds_read_b128 v[96:99], v142 offset:0
	ds_read_b128 v[100:103], v142 offset:2048
	ds_read_b128 v[104:107], v142 offset:4096
	ds_read_b128 v[108:111], v142 offset:6144
	ds_read_b128 v[68:71], v138 offset:2048
	ds_read_b128 v[72:75], v138 offset:4096
	ds_read_b128 v[76:79], v138 offset:6144
	s_waitcnt lgkmcnt(3)
	v_mfma_f32_16x16x32_bf16 v[0:3], v[64:67], v[96:99], v[0:3]
	v_mfma_f32_16x16x32_bf16 v[4:7], v[64:67], v[100:103], v[4:7]
	ds_read_b128 v[80:83], v139 offset:0
	v_mfma_f32_16x16x32_bf16 v[8:11], v[64:67], v[104:107], v[8:11]
	v_mfma_f32_16x16x32_bf16 v[12:15], v[64:67], v[108:111], v[12:15]
	ds_read_b128 v[112:115], v143 offset:0
	s_waitcnt lgkmcnt(4)
	v_mfma_f32_16x16x32_bf16 v[16:19], v[68:71], v[96:99], v[16:19]
	v_mfma_f32_16x16x32_bf16 v[20:23], v[68:71], v[100:103], v[20:23]
	ds_read_b128 v[116:119], v143 offset:2048
	v_mfma_f32_16x16x32_bf16 v[24:27], v[68:71], v[104:107], v[24:27]
	v_mfma_f32_16x16x32_bf16 v[28:31], v[68:71], v[108:111], v[28:31]
	ds_read_b128 v[120:123], v143 offset:4096
	s_waitcnt lgkmcnt(5)
	v_mfma_f32_16x16x32_bf16 v[32:35], v[72:75], v[96:99], v[32:35]
	v_mfma_f32_16x16x32_bf16 v[36:39], v[72:75], v[100:103], v[36:39]
	ds_read_b128 v[124:127], v143 offset:6144
	v_mfma_f32_16x16x32_bf16 v[40:43], v[72:75], v[104:107], v[40:43]
	v_mfma_f32_16x16x32_bf16 v[44:47], v[72:75], v[108:111], v[44:47]
	ds_read_b128 v[84:87], v139 offset:2048
	s_waitcnt lgkmcnt(6)
	v_mfma_f32_16x16x32_bf16 v[48:51], v[76:79], v[96:99], v[48:51]
	v_mfma_f32_16x16x32_bf16 v[52:55], v[76:79], v[100:103], v[52:55]
	ds_read_b128 v[88:91], v139 offset:4096
	v_mfma_f32_16x16x32_bf16 v[56:59], v[76:79], v[104:107], v[56:59]
	v_mfma_f32_16x16x32_bf16 v[60:63], v[76:79], v[108:111], v[60:63]
	ds_read_b128 v[92:95], v139 offset:6144
	s_waitcnt lgkmcnt(3)
	v_mfma_f32_16x16x32_bf16 v[0:3], v[80:83], v[112:115], v[0:3]
	v_mfma_f32_16x16x32_bf16 v[4:7], v[80:83], v[116:119], v[4:7]
	v_mfma_f32_16x16x32_bf16 v[8:11], v[80:83], v[120:123], v[8:11]
	v_mfma_f32_16x16x32_bf16 v[12:15], v[80:83], v[124:127], v[12:15]
	s_waitcnt lgkmcnt(2)
	v_mfma_f32_16x16x32_bf16 v[16:19], v[84:87], v[112:115], v[16:19]
	v_mfma_f32_16x16x32_bf16 v[20:23], v[84:87], v[116:119], v[20:23]
	v_mfma_f32_16x16x32_bf16 v[24:27], v[84:87], v[120:123], v[24:27]
	v_mfma_f32_16x16x32_bf16 v[28:31], v[84:87], v[124:127], v[28:31]
	s_waitcnt lgkmcnt(1)
	v_mfma_f32_16x16x32_bf16 v[32:35], v[88:91], v[112:115], v[32:35]
	v_mfma_f32_16x16x32_bf16 v[36:39], v[88:91], v[116:119], v[36:39]
	v_mfma_f32_16x16x32_bf16 v[40:43], v[88:91], v[120:123], v[40:43]
	v_mfma_f32_16x16x32_bf16 v[44:47], v[88:91], v[124:127], v[44:47]
	s_waitcnt lgkmcnt(0)
	v_mfma_f32_16x16x32_bf16 v[48:51], v[92:95], v[112:115], v[48:51]
	v_mfma_f32_16x16x32_bf16 v[52:55], v[92:95], v[116:119], v[52:55]
	v_mfma_f32_16x16x32_bf16 v[56:59], v[92:95], v[120:123], v[56:59]
	v_mfma_f32_16x16x32_bf16 v[60:63], v[92:95], v[124:127], v[60:63]
	s_waitcnt vmcnt(0)
	s_barrier
	s_add_i32 s99, s99, 1
	s_cmp_eq_u32 s99, 16
	s_movk_i32 s0, 0x80
	s_cselect_b32 s0, 0xfffff880, s0
	s_cselect_b32 s99, 0, s99
	s_ashr_i32 s1, s0, 31
	s_add_u32 s26, s26, s0
	s_addc_u32 s27, s27, s1
	s_add_u32 s28, s28, s0
	s_addc_u32 s29, s29, s1
	s_mov_b32 m0, s7
	s_nop 0
	global_load_lds_dwordx4 v132, s[26:27] offset:0
	global_load_lds_dwordx4 v133, s[26:27] offset:1024
	global_load_lds_dwordx4 v134, s[26:27] offset:2048
	global_load_lds_dwordx4 v135, s[26:27] offset:3072
	s_mov_b32 m0, s8
	s_nop 0
	global_load_lds_dwordx4 v132, s[28:29] offset:0
	global_load_lds_dwordx4 v133, s[28:29] offset:1024
	global_load_lds_dwordx4 v134, s[28:29] offset:2048
	global_load_lds_dwordx4 v135, s[28:29] offset:3072
	ds_read_b128 v[64:67], v136 offset:0
	ds_read_b128 v[96:99], v140 offset:0
	ds_read_b128 v[100:103], v140 offset:2048
	ds_read_b128 v[104:107], v140 offset:4096
	ds_read_b128 v[108:111], v140 offset:6144
	ds_read_b128 v[68:71], v136 offset:2048
	ds_read_b128 v[72:75], v136 offset:4096
	ds_read_b128 v[76:79], v136 offset:6144
	s_waitcnt lgkmcnt(3)
	v_mfma_f32_16x16x32_bf16 v[0:3], v[64:67], v[96:99], v[0:3]
	v_mfma_f32_16x16x32_bf16 v[4:7], v[64:67], v[100:103], v[4:7]
	ds_read_b128 v[80:83], v137 offset:0
	v_mfma_f32_16x16x32_bf16 v[8:11], v[64:67], v[104:107], v[8:11]
	v_mfma_f32_16x16x32_bf16 v[12:15], v[64:67], v[108:111], v[12:15]
	ds_read_b128 v[112:115], v141 offset:0
	s_waitcnt lgkmcnt(4)
	v_mfma_f32_16x16x32_bf16 v[16:19], v[68:71], v[96:99], v[16:19]
	v_mfma_f32_16x16x32_bf16 v[20:23], v[68:71], v[100:103], v[20:23]
	ds_read_b128 v[116:119], v141 offset:2048
	v_mfma_f32_16x16x32_bf16 v[24:27], v[68:71], v[104:107], v[24:27]
	v_mfma_f32_16x16x32_bf16 v[28:31], v[68:71], v[108:111], v[28:31]
	ds_read_b128 v[120:123], v141 offset:4096
	s_waitcnt lgkmcnt(5)
	v_mfma_f32_16x16x32_bf16 v[32:35], v[72:75], v[96:99], v[32:35]
	v_mfma_f32_16x16x32_bf16 v[36:39], v[72:75], v[100:103], v[36:39]
	ds_read_b128 v[124:127], v141 offset:6144
	v_mfma_f32_16x16x32_bf16 v[40:43], v[72:75], v[104:107], v[40:43]
	v_mfma_f32_16x16x32_bf16 v[44:47], v[72:75], v[108:111], v[44:47]
	ds_read_b128 v[84:87], v137 offset:2048
	s_waitcnt lgkmcnt(6)
	v_mfma_f32_16x16x32_bf16 v[48:51], v[76:79], v[96:99], v[48:51]
	v_mfma_f32_16x16x32_bf16 v[52:55], v[76:79], v[100:103], v[52:55]
	ds_read_b128 v[88:91], v137 offset:4096
	v_mfma_f32_16x16x32_bf16 v[56:59], v[76:79], v[104:107], v[56:59]
	v_mfma_f32_16x16x32_bf16 v[60:63], v[76:79], v[108:111], v[60:63]
	ds_read_b128 v[92:95], v137 offset:6144
	s_waitcnt lgkmcnt(3)
	v_mfma_f32_16x16x32_bf16 v[0:3], v[80:83], v[112:115], v[0:3]
	v_mfma_f32_16x16x32_bf16 v[4:7], v[80:83], v[116:119], v[4:7]
	v_mfma_f32_16x16x32_bf16 v[8:11], v[80:83], v[120:123], v[8:11]
	v_mfma_f32_16x16x32_bf16 v[12:15], v[80:83], v[124:127], v[12:15]
	s_waitcnt lgkmcnt(2)
	v_mfma_f32_16x16x32_bf16 v[16:19], v[84:87], v[112:115], v[16:19]
	v_mfma_f32_16x16x32_bf16 v[20:23], v[84:87], v[116:119], v[20:23]
	v_mfma_f32_16x16x32_bf16 v[24:27], v[84:87], v[120:123], v[24:27]
	v_mfma_f32_16x16x32_bf16 v[28:31], v[84:87], v[124:127], v[28:31]
	s_waitcnt lgkmcnt(1)
	v_mfma_f32_16x16x32_bf16 v[32:35], v[88:91], v[112:115], v[32:35]
	v_mfma_f32_16x16x32_bf16 v[36:39], v[88:91], v[116:119], v[36:39]
	v_mfma_f32_16x16x32_bf16 v[40:43], v[88:91], v[120:123], v[40:43]
	v_mfma_f32_16x16x32_bf16 v[44:47], v[88:91], v[124:127], v[44:47]
	s_waitcnt lgkmcnt(0)
	v_mfma_f32_16x16x32_bf16 v[48:51], v[92:95], v[112:115], v[48:51]
	v_mfma_f32_16x16x32_bf16 v[52:55], v[92:95], v[116:119], v[52:55]
	v_mfma_f32_16x16x32_bf16 v[56:59], v[92:95], v[120:123], v[56:59]
	v_mfma_f32_16x16x32_bf16 v[60:63], v[92:95], v[124:127], v[60:63]
	s_waitcnt vmcnt(0)
	s_barrier
	s_add_i32 s99, s99, 1
	s_cmp_eq_u32 s99, 16
	s_movk_i32 s0, 0x80
	s_cselect_b32 s0, 0xfffff880, s0
	s_cselect_b32 s99, 0, s99
	s_ashr_i32 s1, s0, 31
	s_add_u32 s26, s26, s0
	s_addc_u32 s27, s27, s1
	s_add_u32 s28, s28, s0
	s_addc_u32 s29, s29, s1
	s_mov_b32 m0, s5
	s_nop 0
	global_load_lds_dwordx4 v132, s[26:27] offset:0
	global_load_lds_dwordx4 v133, s[26:27] offset:1024
	global_load_lds_dwordx4 v134, s[26:27] offset:2048
	global_load_lds_dwordx4 v135, s[26:27] offset:3072
	s_mov_b32 m0, s6
	s_nop 0
	global_load_lds_dwordx4 v132, s[28:29] offset:0
	global_load_lds_dwordx4 v133, s[28:29] offset:1024
	global_load_lds_dwordx4 v134, s[28:29] offset:2048
	global_load_lds_dwordx4 v135, s[28:29] offset:3072
	ds_read_b128 v[64:67], v138 offset:0
	ds_read_b128 v[96:99], v142 offset:0
	ds_read_b128 v[100:103], v142 offset:2048
	ds_read_b128 v[104:107], v142 offset:4096
	ds_read_b128 v[108:111], v142 offset:6144
	ds_read_b128 v[68:71], v138 offset:2048
	ds_read_b128 v[72:75], v138 offset:4096
	ds_read_b128 v[76:79], v138 offset:6144
	s_waitcnt lgkmcnt(3)
	v_mfma_f32_16x16x32_bf16 v[0:3], v[64:67], v[96:99], v[0:3]
	v_mfma_f32_16x16x32_bf16 v[4:7], v[64:67], v[100:103], v[4:7]
	ds_read_b128 v[80:83], v139 offset:0
	v_mfma_f32_16x16x32_bf16 v[8:11], v[64:67], v[104:107], v[8:11]
	v_mfma_f32_16x16x32_bf16 v[12:15], v[64:67], v[108:111], v[12:15]
	ds_read_b128 v[112:115], v143 offset:0
	s_waitcnt lgkmcnt(4)
	v_mfma_f32_16x16x32_bf16 v[16:19], v[68:71], v[96:99], v[16:19]
	v_mfma_f32_16x16x32_bf16 v[20:23], v[68:71], v[100:103], v[20:23]
	ds_read_b128 v[116:119], v143 offset:2048
	v_mfma_f32_16x16x32_bf16 v[24:27], v[68:71], v[104:107], v[24:27]
	v_mfma_f32_16x16x32_bf16 v[28:31], v[68:71], v[108:111], v[28:31]
	ds_read_b128 v[120:123], v143 offset:4096
	s_waitcnt lgkmcnt(5)
	v_mfma_f32_16x16x32_bf16 v[32:35], v[72:75], v[96:99], v[32:35]
	v_mfma_f32_16x16x32_bf16 v[36:39], v[72:75], v[100:103], v[36:39]
	ds_read_b128 v[124:127], v143 offset:6144
	v_mfma_f32_16x16x32_bf16 v[40:43], v[72:75], v[104:107], v[40:43]
	v_mfma_f32_16x16x32_bf16 v[44:47], v[72:75], v[108:111], v[44:47]
	ds_read_b128 v[84:87], v139 offset:2048
	s_waitcnt lgkmcnt(6)
	v_mfma_f32_16x16x32_bf16 v[48:51], v[76:79], v[96:99], v[48:51]
	v_mfma_f32_16x16x32_bf16 v[52:55], v[76:79], v[100:103], v[52:55]
	ds_read_b128 v[88:91], v139 offset:4096
	v_mfma_f32_16x16x32_bf16 v[56:59], v[76:79], v[104:107], v[56:59]
	v_mfma_f32_16x16x32_bf16 v[60:63], v[76:79], v[108:111], v[60:63]
	ds_read_b128 v[92:95], v139 offset:6144
	s_waitcnt lgkmcnt(3)
	v_mfma_f32_16x16x32_bf16 v[0:3], v[80:83], v[112:115], v[0:3]
	v_mfma_f32_16x16x32_bf16 v[4:7], v[80:83], v[116:119], v[4:7]
	v_mfma_f32_16x16x32_bf16 v[8:11], v[80:83], v[120:123], v[8:11]
	v_mfma_f32_16x16x32_bf16 v[12:15], v[80:83], v[124:127], v[12:15]
	s_waitcnt lgkmcnt(2)
	v_mfma_f32_16x16x32_bf16 v[16:19], v[84:87], v[112:115], v[16:19]
	v_mfma_f32_16x16x32_bf16 v[20:23], v[84:87], v[116:119], v[20:23]
	v_mfma_f32_16x16x32_bf16 v[24:27], v[84:87], v[120:123], v[24:27]
	v_mfma_f32_16x16x32_bf16 v[28:31], v[84:87], v[124:127], v[28:31]
	s_waitcnt lgkmcnt(1)
	v_mfma_f32_16x16x32_bf16 v[32:35], v[88:91], v[112:115], v[32:35]
	v_mfma_f32_16x16x32_bf16 v[36:39], v[88:91], v[116:119], v[36:39]
	v_mfma_f32_16x16x32_bf16 v[40:43], v[88:91], v[120:123], v[40:43]
	v_mfma_f32_16x16x32_bf16 v[44:47], v[88:91], v[124:127], v[44:47]
	s_waitcnt lgkmcnt(0)
	v_mfma_f32_16x16x32_bf16 v[48:51], v[92:95], v[112:115], v[48:51]
	v_mfma_f32_16x16x32_bf16 v[52:55], v[92:95], v[116:119], v[52:55]
	v_mfma_f32_16x16x32_bf16 v[56:59], v[92:95], v[120:123], v[56:59]
	v_mfma_f32_16x16x32_bf16 v[60:63], v[92:95], v[124:127], v[60:63]
	s_waitcnt vmcnt(0)
	s_barrier
	s_add_i32 s99, s99, 1
	s_cmp_eq_u32 s99, 16
	s_movk_i32 s0, 0x80
	s_cselect_b32 s0, 0xfffff880, s0
	s_cselect_b32 s99, 0, s99
	s_ashr_i32 s1, s0, 31
	s_add_u32 s26, s26, s0
	s_addc_u32 s27, s27, s1
	s_add_u32 s28, s28, s0
	s_addc_u32 s29, s29, s1
	s_mov_b32 m0, s7
	s_nop 0
	global_load_lds_dwordx4 v132, s[26:27] offset:0
	global_load_lds_dwordx4 v133, s[26:27] offset:1024
	global_load_lds_dwordx4 v134, s[26:27] offset:2048
	global_load_lds_dwordx4 v135, s[26:27] offset:3072
	s_mov_b32 m0, s8
	s_nop 0
	global_load_lds_dwordx4 v132, s[28:29] offset:0
	global_load_lds_dwordx4 v133, s[28:29] offset:1024
	global_load_lds_dwordx4 v134, s[28:29] offset:2048
	global_load_lds_dwordx4 v135, s[28:29] offset:3072
	ds_read_b128 v[64:67], v136 offset:0
	ds_read_b128 v[96:99], v140 offset:0
	ds_read_b128 v[100:103], v140 offset:2048
	ds_read_b128 v[104:107], v140 offset:4096
	ds_read_b128 v[108:111], v140 offset:6144
	ds_read_b128 v[68:71], v136 offset:2048
	ds_read_b128 v[72:75], v136 offset:4096
	ds_read_b128 v[76:79], v136 offset:6144
	s_waitcnt lgkmcnt(3)
	v_mfma_f32_16x16x32_bf16 v[0:3], v[64:67], v[96:99], v[0:3]
	v_mfma_f32_16x16x32_bf16 v[4:7], v[64:67], v[100:103], v[4:7]
	ds_read_b128 v[80:83], v137 offset:0
	v_mfma_f32_16x16x32_bf16 v[8:11], v[64:67], v[104:107], v[8:11]
	v_mfma_f32_16x16x32_bf16 v[12:15], v[64:67], v[108:111], v[12:15]
	ds_read_b128 v[112:115], v141 offset:0
	s_waitcnt lgkmcnt(4)
	v_mfma_f32_16x16x32_bf16 v[16:19], v[68:71], v[96:99], v[16:19]
	v_mfma_f32_16x16x32_bf16 v[20:23], v[68:71], v[100:103], v[20:23]
	ds_read_b128 v[116:119], v141 offset:2048
	v_mfma_f32_16x16x32_bf16 v[24:27], v[68:71], v[104:107], v[24:27]
	v_mfma_f32_16x16x32_bf16 v[28:31], v[68:71], v[108:111], v[28:31]
	ds_read_b128 v[120:123], v141 offset:4096
	s_waitcnt lgkmcnt(5)
	v_mfma_f32_16x16x32_bf16 v[32:35], v[72:75], v[96:99], v[32:35]
	v_mfma_f32_16x16x32_bf16 v[36:39], v[72:75], v[100:103], v[36:39]
	ds_read_b128 v[124:127], v141 offset:6144
	v_mfma_f32_16x16x32_bf16 v[40:43], v[72:75], v[104:107], v[40:43]
	v_mfma_f32_16x16x32_bf16 v[44:47], v[72:75], v[108:111], v[44:47]
	ds_read_b128 v[84:87], v137 offset:2048
	s_waitcnt lgkmcnt(6)
	v_mfma_f32_16x16x32_bf16 v[48:51], v[76:79], v[96:99], v[48:51]
	v_mfma_f32_16x16x32_bf16 v[52:55], v[76:79], v[100:103], v[52:55]
	ds_read_b128 v[88:91], v137 offset:4096
	v_mfma_f32_16x16x32_bf16 v[56:59], v[76:79], v[104:107], v[56:59]
	v_mfma_f32_16x16x32_bf16 v[60:63], v[76:79], v[108:111], v[60:63]
	ds_read_b128 v[92:95], v137 offset:6144
	s_waitcnt lgkmcnt(3)
	v_mfma_f32_16x16x32_bf16 v[0:3], v[80:83], v[112:115], v[0:3]
	v_mfma_f32_16x16x32_bf16 v[4:7], v[80:83], v[116:119], v[4:7]
	v_mfma_f32_16x16x32_bf16 v[8:11], v[80:83], v[120:123], v[8:11]
	v_mfma_f32_16x16x32_bf16 v[12:15], v[80:83], v[124:127], v[12:15]
	s_waitcnt lgkmcnt(2)
	v_mfma_f32_16x16x32_bf16 v[16:19], v[84:87], v[112:115], v[16:19]
	v_mfma_f32_16x16x32_bf16 v[20:23], v[84:87], v[116:119], v[20:23]
	v_mfma_f32_16x16x32_bf16 v[24:27], v[84:87], v[120:123], v[24:27]
	v_mfma_f32_16x16x32_bf16 v[28:31], v[84:87], v[124:127], v[28:31]
	s_waitcnt lgkmcnt(1)
	v_mfma_f32_16x16x32_bf16 v[32:35], v[88:91], v[112:115], v[32:35]
	v_mfma_f32_16x16x32_bf16 v[36:39], v[88:91], v[116:119], v[36:39]
	v_mfma_f32_16x16x32_bf16 v[40:43], v[88:91], v[120:123], v[40:43]
	v_mfma_f32_16x16x32_bf16 v[44:47], v[88:91], v[124:127], v[44:47]
	s_waitcnt lgkmcnt(0)
	v_mfma_f32_16x16x32_bf16 v[48:51], v[92:95], v[112:115], v[48:51]
	v_mfma_f32_16x16x32_bf16 v[52:55], v[92:95], v[116:119], v[52:55]
	v_mfma_f32_16x16x32_bf16 v[56:59], v[92:95], v[120:123], v[56:59]
	v_mfma_f32_16x16x32_bf16 v[60:63], v[92:95], v[124:127], v[60:63]
	s_waitcnt vmcnt(0)
	s_barrier
	s_add_i32 s99, s99, 1
	s_cmp_eq_u32 s99, 16
	s_movk_i32 s0, 0x80
	s_cselect_b32 s0, 0xfffff880, s0
	s_cselect_b32 s99, 0, s99
	s_ashr_i32 s1, s0, 31
	s_add_u32 s26, s26, s0
	s_addc_u32 s27, s27, s1
	s_add_u32 s28, s28, s0
	s_addc_u32 s29, s29, s1
	s_mov_b32 m0, s5
	s_nop 0
	global_load_lds_dwordx4 v132, s[26:27] offset:0
	global_load_lds_dwordx4 v133, s[26:27] offset:1024
	global_load_lds_dwordx4 v134, s[26:27] offset:2048
	global_load_lds_dwordx4 v135, s[26:27] offset:3072
	s_mov_b32 m0, s6
	s_nop 0
	global_load_lds_dwordx4 v132, s[28:29] offset:0
	global_load_lds_dwordx4 v133, s[28:29] offset:1024
	global_load_lds_dwordx4 v134, s[28:29] offset:2048
	global_load_lds_dwordx4 v135, s[28:29] offset:3072
	ds_read_b128 v[64:67], v138 offset:0
	ds_read_b128 v[96:99], v142 offset:0
	ds_read_b128 v[100:103], v142 offset:2048
	ds_read_b128 v[104:107], v142 offset:4096
	ds_read_b128 v[108:111], v142 offset:6144
	ds_read_b128 v[68:71], v138 offset:2048
	ds_read_b128 v[72:75], v138 offset:4096
	ds_read_b128 v[76:79], v138 offset:6144
	s_waitcnt lgkmcnt(3)
	v_mfma_f32_16x16x32_bf16 v[0:3], v[64:67], v[96:99], v[0:3]
	v_mfma_f32_16x16x32_bf16 v[4:7], v[64:67], v[100:103], v[4:7]
	ds_read_b128 v[80:83], v139 offset:0
	v_mfma_f32_16x16x32_bf16 v[8:11], v[64:67], v[104:107], v[8:11]
	v_mfma_f32_16x16x32_bf16 v[12:15], v[64:67], v[108:111], v[12:15]
	ds_read_b128 v[112:115], v143 offset:0
	s_waitcnt lgkmcnt(4)
	v_mfma_f32_16x16x32_bf16 v[16:19], v[68:71], v[96:99], v[16:19]
	v_mfma_f32_16x16x32_bf16 v[20:23], v[68:71], v[100:103], v[20:23]
	ds_read_b128 v[116:119], v143 offset:2048
	v_mfma_f32_16x16x32_bf16 v[24:27], v[68:71], v[104:107], v[24:27]
	v_mfma_f32_16x16x32_bf16 v[28:31], v[68:71], v[108:111], v[28:31]
	ds_read_b128 v[120:123], v143 offset:4096
	s_waitcnt lgkmcnt(5)
	v_mfma_f32_16x16x32_bf16 v[32:35], v[72:75], v[96:99], v[32:35]
	v_mfma_f32_16x16x32_bf16 v[36:39], v[72:75], v[100:103], v[36:39]
	ds_read_b128 v[124:127], v143 offset:6144
	v_mfma_f32_16x16x32_bf16 v[40:43], v[72:75], v[104:107], v[40:43]
	v_mfma_f32_16x16x32_bf16 v[44:47], v[72:75], v[108:111], v[44:47]
	ds_read_b128 v[84:87], v139 offset:2048
	s_waitcnt lgkmcnt(6)
	v_mfma_f32_16x16x32_bf16 v[48:51], v[76:79], v[96:99], v[48:51]
	v_mfma_f32_16x16x32_bf16 v[52:55], v[76:79], v[100:103], v[52:55]
	ds_read_b128 v[88:91], v139 offset:4096
	v_mfma_f32_16x16x32_bf16 v[56:59], v[76:79], v[104:107], v[56:59]
	v_mfma_f32_16x16x32_bf16 v[60:63], v[76:79], v[108:111], v[60:63]
	ds_read_b128 v[92:95], v139 offset:6144
	s_waitcnt lgkmcnt(3)
	v_mfma_f32_16x16x32_bf16 v[0:3], v[80:83], v[112:115], v[0:3]
	v_mfma_f32_16x16x32_bf16 v[4:7], v[80:83], v[116:119], v[4:7]
	v_mfma_f32_16x16x32_bf16 v[8:11], v[80:83], v[120:123], v[8:11]
	v_mfma_f32_16x16x32_bf16 v[12:15], v[80:83], v[124:127], v[12:15]
	s_waitcnt lgkmcnt(2)
	v_mfma_f32_16x16x32_bf16 v[16:19], v[84:87], v[112:115], v[16:19]
	v_mfma_f32_16x16x32_bf16 v[20:23], v[84:87], v[116:119], v[20:23]
	v_mfma_f32_16x16x32_bf16 v[24:27], v[84:87], v[120:123], v[24:27]
	v_mfma_f32_16x16x32_bf16 v[28:31], v[84:87], v[124:127], v[28:31]
	s_waitcnt lgkmcnt(1)
	v_mfma_f32_16x16x32_bf16 v[32:35], v[88:91], v[112:115], v[32:35]
	v_mfma_f32_16x16x32_bf16 v[36:39], v[88:91], v[116:119], v[36:39]
	v_mfma_f32_16x16x32_bf16 v[40:43], v[88:91], v[120:123], v[40:43]
	v_mfma_f32_16x16x32_bf16 v[44:47], v[88:91], v[124:127], v[44:47]
	s_waitcnt lgkmcnt(0)
	v_mfma_f32_16x16x32_bf16 v[48:51], v[92:95], v[112:115], v[48:51]
	v_mfma_f32_16x16x32_bf16 v[52:55], v[92:95], v[116:119], v[52:55]
	v_mfma_f32_16x16x32_bf16 v[56:59], v[92:95], v[120:123], v[56:59]
	v_mfma_f32_16x16x32_bf16 v[60:63], v[92:95], v[124:127], v[60:63]
	s_waitcnt vmcnt(0)
	s_barrier
	s_add_i32 s99, s99, 1
	s_cmp_eq_u32 s99, 16
	s_movk_i32 s0, 0x80
	s_cselect_b32 s0, 0xfffff880, s0
	s_cselect_b32 s99, 0, s99
	s_ashr_i32 s1, s0, 31
	s_add_u32 s26, s26, s0
	s_addc_u32 s27, s27, s1
	s_add_u32 s28, s28, s0
	s_addc_u32 s29, s29, s1
	s_mov_b32 m0, s7
	s_nop 0
	global_load_lds_dwordx4 v132, s[26:27] offset:0
	global_load_lds_dwordx4 v133, s[26:27] offset:1024
	global_load_lds_dwordx4 v134, s[26:27] offset:2048
	global_load_lds_dwordx4 v135, s[26:27] offset:3072
	s_mov_b32 m0, s8
	s_nop 0
	global_load_lds_dwordx4 v132, s[28:29] offset:0
	global_load_lds_dwordx4 v133, s[28:29] offset:1024
	global_load_lds_dwordx4 v134, s[28:29] offset:2048
	global_load_lds_dwordx4 v135, s[28:29] offset:3072
	ds_read_b128 v[64:67], v136 offset:0
	ds_read_b128 v[96:99], v140 offset:0
	ds_read_b128 v[100:103], v140 offset:2048
	ds_read_b128 v[104:107], v140 offset:4096
	ds_read_b128 v[108:111], v140 offset:6144
	ds_read_b128 v[68:71], v136 offset:2048
	ds_read_b128 v[72:75], v136 offset:4096
	ds_read_b128 v[76:79], v136 offset:6144
	s_waitcnt lgkmcnt(3)
	v_mfma_f32_16x16x32_bf16 v[0:3], v[64:67], v[96:99], v[0:3]
	v_mfma_f32_16x16x32_bf16 v[4:7], v[64:67], v[100:103], v[4:7]
	ds_read_b128 v[80:83], v137 offset:0
	v_mfma_f32_16x16x32_bf16 v[8:11], v[64:67], v[104:107], v[8:11]
	v_mfma_f32_16x16x32_bf16 v[12:15], v[64:67], v[108:111], v[12:15]
	ds_read_b128 v[112:115], v141 offset:0
	s_waitcnt lgkmcnt(4)
	v_mfma_f32_16x16x32_bf16 v[16:19], v[68:71], v[96:99], v[16:19]
	v_mfma_f32_16x16x32_bf16 v[20:23], v[68:71], v[100:103], v[20:23]
	ds_read_b128 v[116:119], v141 offset:2048
	v_mfma_f32_16x16x32_bf16 v[24:27], v[68:71], v[104:107], v[24:27]
	v_mfma_f32_16x16x32_bf16 v[28:31], v[68:71], v[108:111], v[28:31]
	ds_read_b128 v[120:123], v141 offset:4096
	s_waitcnt lgkmcnt(5)
	v_mfma_f32_16x16x32_bf16 v[32:35], v[72:75], v[96:99], v[32:35]
	v_mfma_f32_16x16x32_bf16 v[36:39], v[72:75], v[100:103], v[36:39]
	ds_read_b128 v[124:127], v141 offset:6144
	v_mfma_f32_16x16x32_bf16 v[40:43], v[72:75], v[104:107], v[40:43]
	v_mfma_f32_16x16x32_bf16 v[44:47], v[72:75], v[108:111], v[44:47]
	ds_read_b128 v[84:87], v137 offset:2048
	s_waitcnt lgkmcnt(6)
	v_mfma_f32_16x16x32_bf16 v[48:51], v[76:79], v[96:99], v[48:51]
	v_mfma_f32_16x16x32_bf16 v[52:55], v[76:79], v[100:103], v[52:55]
	ds_read_b128 v[88:91], v137 offset:4096
	v_mfma_f32_16x16x32_bf16 v[56:59], v[76:79], v[104:107], v[56:59]
	v_mfma_f32_16x16x32_bf16 v[60:63], v[76:79], v[108:111], v[60:63]
	ds_read_b128 v[92:95], v137 offset:6144
	s_waitcnt lgkmcnt(3)
	v_mfma_f32_16x16x32_bf16 v[0:3], v[80:83], v[112:115], v[0:3]
	v_mfma_f32_16x16x32_bf16 v[4:7], v[80:83], v[116:119], v[4:7]
	v_mfma_f32_16x16x32_bf16 v[8:11], v[80:83], v[120:123], v[8:11]
	v_mfma_f32_16x16x32_bf16 v[12:15], v[80:83], v[124:127], v[12:15]
	s_waitcnt lgkmcnt(2)
	v_mfma_f32_16x16x32_bf16 v[16:19], v[84:87], v[112:115], v[16:19]
	v_mfma_f32_16x16x32_bf16 v[20:23], v[84:87], v[116:119], v[20:23]
	v_mfma_f32_16x16x32_bf16 v[24:27], v[84:87], v[120:123], v[24:27]
	v_mfma_f32_16x16x32_bf16 v[28:31], v[84:87], v[124:127], v[28:31]
	s_waitcnt lgkmcnt(1)
	v_mfma_f32_16x16x32_bf16 v[32:35], v[88:91], v[112:115], v[32:35]
	v_mfma_f32_16x16x32_bf16 v[36:39], v[88:91], v[116:119], v[36:39]
	v_mfma_f32_16x16x32_bf16 v[40:43], v[88:91], v[120:123], v[40:43]
	v_mfma_f32_16x16x32_bf16 v[44:47], v[88:91], v[124:127], v[44:47]
	s_waitcnt lgkmcnt(0)
	v_mfma_f32_16x16x32_bf16 v[48:51], v[92:95], v[112:115], v[48:51]
	v_mfma_f32_16x16x32_bf16 v[52:55], v[92:95], v[116:119], v[52:55]
	v_mfma_f32_16x16x32_bf16 v[56:59], v[92:95], v[120:123], v[56:59]
	v_mfma_f32_16x16x32_bf16 v[60:63], v[92:95], v[124:127], v[60:63]
	s_waitcnt vmcnt(0)
	s_barrier
	s_add_i32 s99, s99, 1
	s_cmp_eq_u32 s99, 16
	s_movk_i32 s0, 0x80
	s_cselect_b32 s0, 0xfffff880, s0
	s_cselect_b32 s99, 0, s99
	s_ashr_i32 s1, s0, 31
	s_add_u32 s26, s26, s0
	s_addc_u32 s27, s27, s1
	s_add_u32 s28, s28, s0
	s_addc_u32 s29, s29, s1
	s_mov_b32 m0, s5
	s_nop 0
	global_load_lds_dwordx4 v132, s[26:27] offset:0
	global_load_lds_dwordx4 v133, s[26:27] offset:1024
	global_load_lds_dwordx4 v134, s[26:27] offset:2048
	global_load_lds_dwordx4 v135, s[26:27] offset:3072
	s_mov_b32 m0, s6
	s_nop 0
	global_load_lds_dwordx4 v132, s[28:29] offset:0
	global_load_lds_dwordx4 v133, s[28:29] offset:1024
	global_load_lds_dwordx4 v134, s[28:29] offset:2048
	global_load_lds_dwordx4 v135, s[28:29] offset:3072
	ds_read_b128 v[64:67], v138 offset:0
	ds_read_b128 v[96:99], v142 offset:0
	ds_read_b128 v[100:103], v142 offset:2048
	ds_read_b128 v[104:107], v142 offset:4096
	ds_read_b128 v[108:111], v142 offset:6144
	ds_read_b128 v[68:71], v138 offset:2048
	ds_read_b128 v[72:75], v138 offset:4096
	ds_read_b128 v[76:79], v138 offset:6144
	s_waitcnt lgkmcnt(3)
	v_mfma_f32_16x16x32_bf16 v[0:3], v[64:67], v[96:99], v[0:3]
	v_mfma_f32_16x16x32_bf16 v[4:7], v[64:67], v[100:103], v[4:7]
	ds_read_b128 v[80:83], v139 offset:0
	v_mfma_f32_16x16x32_bf16 v[8:11], v[64:67], v[104:107], v[8:11]
	v_mfma_f32_16x16x32_bf16 v[12:15], v[64:67], v[108:111], v[12:15]
	ds_read_b128 v[112:115], v143 offset:0
	s_waitcnt lgkmcnt(4)
	v_mfma_f32_16x16x32_bf16 v[16:19], v[68:71], v[96:99], v[16:19]
	v_mfma_f32_16x16x32_bf16 v[20:23], v[68:71], v[100:103], v[20:23]
	ds_read_b128 v[116:119], v143 offset:2048
	v_mfma_f32_16x16x32_bf16 v[24:27], v[68:71], v[104:107], v[24:27]
	v_mfma_f32_16x16x32_bf16 v[28:31], v[68:71], v[108:111], v[28:31]
	ds_read_b128 v[120:123], v143 offset:4096
	s_waitcnt lgkmcnt(5)
	v_mfma_f32_16x16x32_bf16 v[32:35], v[72:75], v[96:99], v[32:35]
	v_mfma_f32_16x16x32_bf16 v[36:39], v[72:75], v[100:103], v[36:39]
	ds_read_b128 v[124:127], v143 offset:6144
	v_mfma_f32_16x16x32_bf16 v[40:43], v[72:75], v[104:107], v[40:43]
	v_mfma_f32_16x16x32_bf16 v[44:47], v[72:75], v[108:111], v[44:47]
	ds_read_b128 v[84:87], v139 offset:2048
	s_waitcnt lgkmcnt(6)
	v_mfma_f32_16x16x32_bf16 v[48:51], v[76:79], v[96:99], v[48:51]
	v_mfma_f32_16x16x32_bf16 v[52:55], v[76:79], v[100:103], v[52:55]
	ds_read_b128 v[88:91], v139 offset:4096
	v_mfma_f32_16x16x32_bf16 v[56:59], v[76:79], v[104:107], v[56:59]
	v_mfma_f32_16x16x32_bf16 v[60:63], v[76:79], v[108:111], v[60:63]
	ds_read_b128 v[92:95], v139 offset:6144
	s_waitcnt lgkmcnt(3)
	v_mfma_f32_16x16x32_bf16 v[0:3], v[80:83], v[112:115], v[0:3]
	v_mfma_f32_16x16x32_bf16 v[4:7], v[80:83], v[116:119], v[4:7]
	v_mfma_f32_16x16x32_bf16 v[8:11], v[80:83], v[120:123], v[8:11]
	v_mfma_f32_16x16x32_bf16 v[12:15], v[80:83], v[124:127], v[12:15]
	s_waitcnt lgkmcnt(2)
	v_mfma_f32_16x16x32_bf16 v[16:19], v[84:87], v[112:115], v[16:19]
	v_mfma_f32_16x16x32_bf16 v[20:23], v[84:87], v[116:119], v[20:23]
	v_mfma_f32_16x16x32_bf16 v[24:27], v[84:87], v[120:123], v[24:27]
	v_mfma_f32_16x16x32_bf16 v[28:31], v[84:87], v[124:127], v[28:31]
	s_waitcnt lgkmcnt(1)
	v_mfma_f32_16x16x32_bf16 v[32:35], v[88:91], v[112:115], v[32:35]
	v_mfma_f32_16x16x32_bf16 v[36:39], v[88:91], v[116:119], v[36:39]
	v_mfma_f32_16x16x32_bf16 v[40:43], v[88:91], v[120:123], v[40:43]
	v_mfma_f32_16x16x32_bf16 v[44:47], v[88:91], v[124:127], v[44:47]
	s_waitcnt lgkmcnt(0)
	v_mfma_f32_16x16x32_bf16 v[48:51], v[92:95], v[112:115], v[48:51]
	v_mfma_f32_16x16x32_bf16 v[52:55], v[92:95], v[116:119], v[52:55]
	v_mfma_f32_16x16x32_bf16 v[56:59], v[92:95], v[120:123], v[56:59]
	v_mfma_f32_16x16x32_bf16 v[60:63], v[92:95], v[124:127], v[60:63]
	s_waitcnt vmcnt(0)
	s_barrier
	s_add_i32 s99, s99, 1
	s_cmp_eq_u32 s99, 16
	s_movk_i32 s0, 0x80
	s_cselect_b32 s0, 0xfffff880, s0
	s_cselect_b32 s99, 0, s99
	s_ashr_i32 s1, s0, 31
	s_add_u32 s26, s26, s0
	s_addc_u32 s27, s27, s1
	s_add_u32 s28, s28, s0
	s_addc_u32 s29, s29, s1
	s_mov_b32 m0, s7
	s_nop 0
	global_load_lds_dwordx4 v132, s[26:27] offset:0
	global_load_lds_dwordx4 v133, s[26:27] offset:1024
	global_load_lds_dwordx4 v134, s[26:27] offset:2048
	global_load_lds_dwordx4 v135, s[26:27] offset:3072
	s_mov_b32 m0, s8
	s_nop 0
	global_load_lds_dwordx4 v132, s[28:29] offset:0
	global_load_lds_dwordx4 v133, s[28:29] offset:1024
	global_load_lds_dwordx4 v134, s[28:29] offset:2048
	global_load_lds_dwordx4 v135, s[28:29] offset:3072
	ds_read_b128 v[64:67], v136 offset:0
	ds_read_b128 v[96:99], v140 offset:0
	ds_read_b128 v[100:103], v140 offset:2048
	ds_read_b128 v[104:107], v140 offset:4096
	ds_read_b128 v[108:111], v140 offset:6144
	ds_read_b128 v[68:71], v136 offset:2048
	ds_read_b128 v[72:75], v136 offset:4096
	ds_read_b128 v[76:79], v136 offset:6144
	s_waitcnt lgkmcnt(3)
	v_mfma_f32_16x16x32_bf16 v[0:3], v[64:67], v[96:99], v[0:3]
	v_mfma_f32_16x16x32_bf16 v[4:7], v[64:67], v[100:103], v[4:7]
	ds_read_b128 v[80:83], v137 offset:0
	v_mfma_f32_16x16x32_bf16 v[8:11], v[64:67], v[104:107], v[8:11]
	v_mfma_f32_16x16x32_bf16 v[12:15], v[64:67], v[108:111], v[12:15]
	ds_read_b128 v[112:115], v141 offset:0
	s_waitcnt lgkmcnt(4)
	v_mfma_f32_16x16x32_bf16 v[16:19], v[68:71], v[96:99], v[16:19]
	v_mfma_f32_16x16x32_bf16 v[20:23], v[68:71], v[100:103], v[20:23]
	ds_read_b128 v[116:119], v141 offset:2048
	v_mfma_f32_16x16x32_bf16 v[24:27], v[68:71], v[104:107], v[24:27]
	v_mfma_f32_16x16x32_bf16 v[28:31], v[68:71], v[108:111], v[28:31]
	ds_read_b128 v[120:123], v141 offset:4096
	s_waitcnt lgkmcnt(5)
	v_mfma_f32_16x16x32_bf16 v[32:35], v[72:75], v[96:99], v[32:35]
	v_mfma_f32_16x16x32_bf16 v[36:39], v[72:75], v[100:103], v[36:39]
	ds_read_b128 v[124:127], v141 offset:6144
	v_mfma_f32_16x16x32_bf16 v[40:43], v[72:75], v[104:107], v[40:43]
	v_mfma_f32_16x16x32_bf16 v[44:47], v[72:75], v[108:111], v[44:47]
	ds_read_b128 v[84:87], v137 offset:2048
	s_waitcnt lgkmcnt(6)
	v_mfma_f32_16x16x32_bf16 v[48:51], v[76:79], v[96:99], v[48:51]
	v_mfma_f32_16x16x32_bf16 v[52:55], v[76:79], v[100:103], v[52:55]
	ds_read_b128 v[88:91], v137 offset:4096
	v_mfma_f32_16x16x32_bf16 v[56:59], v[76:79], v[104:107], v[56:59]
	v_mfma_f32_16x16x32_bf16 v[60:63], v[76:79], v[108:111], v[60:63]
	ds_read_b128 v[92:95], v137 offset:6144
	s_waitcnt lgkmcnt(3)
	v_mfma_f32_16x16x32_bf16 v[0:3], v[80:83], v[112:115], v[0:3]
	v_mfma_f32_16x16x32_bf16 v[4:7], v[80:83], v[116:119], v[4:7]
	v_mfma_f32_16x16x32_bf16 v[8:11], v[80:83], v[120:123], v[8:11]
	v_mfma_f32_16x16x32_bf16 v[12:15], v[80:83], v[124:127], v[12:15]
	s_waitcnt lgkmcnt(2)
	v_mfma_f32_16x16x32_bf16 v[16:19], v[84:87], v[112:115], v[16:19]
	v_mfma_f32_16x16x32_bf16 v[20:23], v[84:87], v[116:119], v[20:23]
	v_mfma_f32_16x16x32_bf16 v[24:27], v[84:87], v[120:123], v[24:27]
	v_mfma_f32_16x16x32_bf16 v[28:31], v[84:87], v[124:127], v[28:31]
	s_waitcnt lgkmcnt(1)
	v_mfma_f32_16x16x32_bf16 v[32:35], v[88:91], v[112:115], v[32:35]
	v_mfma_f32_16x16x32_bf16 v[36:39], v[88:91], v[116:119], v[36:39]
	v_mfma_f32_16x16x32_bf16 v[40:43], v[88:91], v[120:123], v[40:43]
	v_mfma_f32_16x16x32_bf16 v[44:47], v[88:91], v[124:127], v[44:47]
	s_waitcnt lgkmcnt(0)
	v_mfma_f32_16x16x32_bf16 v[48:51], v[92:95], v[112:115], v[48:51]
	v_mfma_f32_16x16x32_bf16 v[52:55], v[92:95], v[116:119], v[52:55]
	v_mfma_f32_16x16x32_bf16 v[56:59], v[92:95], v[120:123], v[56:59]
	v_mfma_f32_16x16x32_bf16 v[60:63], v[92:95], v[124:127], v[60:63]
	s_waitcnt vmcnt(0)
	s_barrier
	s_add_i32 s99, s99, 1
	s_cmp_eq_u32 s99, 16
	s_movk_i32 s0, 0x80
	s_cselect_b32 s0, 0xfffff880, s0
	s_cselect_b32 s99, 0, s99
	s_ashr_i32 s1, s0, 31
	s_add_u32 s26, s26, s0
	s_addc_u32 s27, s27, s1
	s_add_u32 s28, s28, s0
	s_addc_u32 s29, s29, s1
	s_mov_b32 m0, s5
	s_nop 0
	global_load_lds_dwordx4 v132, s[26:27] offset:0
	global_load_lds_dwordx4 v133, s[26:27] offset:1024
	global_load_lds_dwordx4 v134, s[26:27] offset:2048
	global_load_lds_dwordx4 v135, s[26:27] offset:3072
	s_mov_b32 m0, s6
	s_nop 0
	global_load_lds_dwordx4 v132, s[28:29] offset:0
	global_load_lds_dwordx4 v133, s[28:29] offset:1024
	global_load_lds_dwordx4 v134, s[28:29] offset:2048
	global_load_lds_dwordx4 v135, s[28:29] offset:3072
	ds_read_b128 v[64:67], v138 offset:0
	ds_read_b128 v[96:99], v142 offset:0
	ds_read_b128 v[100:103], v142 offset:2048
	ds_read_b128 v[104:107], v142 offset:4096
	ds_read_b128 v[108:111], v142 offset:6144
	ds_read_b128 v[68:71], v138 offset:2048
	ds_read_b128 v[72:75], v138 offset:4096
	ds_read_b128 v[76:79], v138 offset:6144
	s_waitcnt lgkmcnt(3)
	v_mfma_f32_16x16x32_bf16 v[0:3], v[64:67], v[96:99], v[0:3]
	v_mfma_f32_16x16x32_bf16 v[4:7], v[64:67], v[100:103], v[4:7]
	ds_read_b128 v[80:83], v139 offset:0
	v_mfma_f32_16x16x32_bf16 v[8:11], v[64:67], v[104:107], v[8:11]
	v_mfma_f32_16x16x32_bf16 v[12:15], v[64:67], v[108:111], v[12:15]
	ds_read_b128 v[112:115], v143 offset:0
	s_waitcnt lgkmcnt(4)
	v_mfma_f32_16x16x32_bf16 v[16:19], v[68:71], v[96:99], v[16:19]
	v_mfma_f32_16x16x32_bf16 v[20:23], v[68:71], v[100:103], v[20:23]
	ds_read_b128 v[116:119], v143 offset:2048
	v_mfma_f32_16x16x32_bf16 v[24:27], v[68:71], v[104:107], v[24:27]
	v_mfma_f32_16x16x32_bf16 v[28:31], v[68:71], v[108:111], v[28:31]
	ds_read_b128 v[120:123], v143 offset:4096
	s_waitcnt lgkmcnt(5)
	v_mfma_f32_16x16x32_bf16 v[32:35], v[72:75], v[96:99], v[32:35]
	v_mfma_f32_16x16x32_bf16 v[36:39], v[72:75], v[100:103], v[36:39]
	ds_read_b128 v[124:127], v143 offset:6144
	v_mfma_f32_16x16x32_bf16 v[40:43], v[72:75], v[104:107], v[40:43]
	v_mfma_f32_16x16x32_bf16 v[44:47], v[72:75], v[108:111], v[44:47]
	ds_read_b128 v[84:87], v139 offset:2048
	s_waitcnt lgkmcnt(6)
	v_mfma_f32_16x16x32_bf16 v[48:51], v[76:79], v[96:99], v[48:51]
	v_mfma_f32_16x16x32_bf16 v[52:55], v[76:79], v[100:103], v[52:55]
	ds_read_b128 v[88:91], v139 offset:4096
	v_mfma_f32_16x16x32_bf16 v[56:59], v[76:79], v[104:107], v[56:59]
	v_mfma_f32_16x16x32_bf16 v[60:63], v[76:79], v[108:111], v[60:63]
	ds_read_b128 v[92:95], v139 offset:6144
	s_waitcnt lgkmcnt(3)
	v_mfma_f32_16x16x32_bf16 v[0:3], v[80:83], v[112:115], v[0:3]
	v_mfma_f32_16x16x32_bf16 v[4:7], v[80:83], v[116:119], v[4:7]
	v_mfma_f32_16x16x32_bf16 v[8:11], v[80:83], v[120:123], v[8:11]
	v_mfma_f32_16x16x32_bf16 v[12:15], v[80:83], v[124:127], v[12:15]
	s_waitcnt lgkmcnt(2)
	v_mfma_f32_16x16x32_bf16 v[16:19], v[84:87], v[112:115], v[16:19]
	v_mfma_f32_16x16x32_bf16 v[20:23], v[84:87], v[116:119], v[20:23]
	v_mfma_f32_16x16x32_bf16 v[24:27], v[84:87], v[120:123], v[24:27]
	v_mfma_f32_16x16x32_bf16 v[28:31], v[84:87], v[124:127], v[28:31]
	s_waitcnt lgkmcnt(1)
	v_mfma_f32_16x16x32_bf16 v[32:35], v[88:91], v[112:115], v[32:35]
	v_mfma_f32_16x16x32_bf16 v[36:39], v[88:91], v[116:119], v[36:39]
	v_mfma_f32_16x16x32_bf16 v[40:43], v[88:91], v[120:123], v[40:43]
	v_mfma_f32_16x16x32_bf16 v[44:47], v[88:91], v[124:127], v[44:47]
	s_waitcnt lgkmcnt(0)
	v_mfma_f32_16x16x32_bf16 v[48:51], v[92:95], v[112:115], v[48:51]
	v_mfma_f32_16x16x32_bf16 v[52:55], v[92:95], v[116:119], v[52:55]
	v_mfma_f32_16x16x32_bf16 v[56:59], v[92:95], v[120:123], v[56:59]
	v_mfma_f32_16x16x32_bf16 v[60:63], v[92:95], v[124:127], v[60:63]
	s_waitcnt vmcnt(0)
	s_barrier
	s_add_i32 s99, s99, 1
	s_cmp_eq_u32 s99, 16
	s_movk_i32 s0, 0x80
	s_cselect_b32 s0, 0xfffff880, s0
	s_cselect_b32 s99, 0, s99
	s_ashr_i32 s1, s0, 31
	s_add_u32 s26, s26, s0
	s_addc_u32 s27, s27, s1
	s_add_u32 s28, s28, s0
	s_addc_u32 s29, s29, s1
	s_mov_b32 m0, s7
	s_nop 0
	global_load_lds_dwordx4 v132, s[26:27] offset:0
	global_load_lds_dwordx4 v133, s[26:27] offset:1024
	global_load_lds_dwordx4 v134, s[26:27] offset:2048
	global_load_lds_dwordx4 v135, s[26:27] offset:3072
	s_mov_b32 m0, s8
	s_nop 0
	global_load_lds_dwordx4 v132, s[28:29] offset:0
	global_load_lds_dwordx4 v133, s[28:29] offset:1024
	global_load_lds_dwordx4 v134, s[28:29] offset:2048
	global_load_lds_dwordx4 v135, s[28:29] offset:3072
	ds_read_b128 v[64:67], v136 offset:0
	ds_read_b128 v[96:99], v140 offset:0
	ds_read_b128 v[100:103], v140 offset:2048
	ds_read_b128 v[104:107], v140 offset:4096
	ds_read_b128 v[108:111], v140 offset:6144
	ds_read_b128 v[68:71], v136 offset:2048
	ds_read_b128 v[72:75], v136 offset:4096
	ds_read_b128 v[76:79], v136 offset:6144
	s_waitcnt lgkmcnt(3)
	v_mfma_f32_16x16x32_bf16 v[0:3], v[64:67], v[96:99], v[0:3]
	v_mfma_f32_16x16x32_bf16 v[4:7], v[64:67], v[100:103], v[4:7]
	ds_read_b128 v[80:83], v137 offset:0
	v_mfma_f32_16x16x32_bf16 v[8:11], v[64:67], v[104:107], v[8:11]
	v_mfma_f32_16x16x32_bf16 v[12:15], v[64:67], v[108:111], v[12:15]
	ds_read_b128 v[112:115], v141 offset:0
	s_waitcnt lgkmcnt(4)
	v_mfma_f32_16x16x32_bf16 v[16:19], v[68:71], v[96:99], v[16:19]
	v_mfma_f32_16x16x32_bf16 v[20:23], v[68:71], v[100:103], v[20:23]
	ds_read_b128 v[116:119], v141 offset:2048
	v_mfma_f32_16x16x32_bf16 v[24:27], v[68:71], v[104:107], v[24:27]
	v_mfma_f32_16x16x32_bf16 v[28:31], v[68:71], v[108:111], v[28:31]
	ds_read_b128 v[120:123], v141 offset:4096
	s_waitcnt lgkmcnt(5)
	v_mfma_f32_16x16x32_bf16 v[32:35], v[72:75], v[96:99], v[32:35]
	v_mfma_f32_16x16x32_bf16 v[36:39], v[72:75], v[100:103], v[36:39]
	ds_read_b128 v[124:127], v141 offset:6144
	v_mfma_f32_16x16x32_bf16 v[40:43], v[72:75], v[104:107], v[40:43]
	v_mfma_f32_16x16x32_bf16 v[44:47], v[72:75], v[108:111], v[44:47]
	ds_read_b128 v[84:87], v137 offset:2048
	s_waitcnt lgkmcnt(6)
	v_mfma_f32_16x16x32_bf16 v[48:51], v[76:79], v[96:99], v[48:51]
	v_mfma_f32_16x16x32_bf16 v[52:55], v[76:79], v[100:103], v[52:55]
	ds_read_b128 v[88:91], v137 offset:4096
	v_mfma_f32_16x16x32_bf16 v[56:59], v[76:79], v[104:107], v[56:59]
	v_mfma_f32_16x16x32_bf16 v[60:63], v[76:79], v[108:111], v[60:63]
	ds_read_b128 v[92:95], v137 offset:6144
	s_waitcnt lgkmcnt(3)
	v_mfma_f32_16x16x32_bf16 v[0:3], v[80:83], v[112:115], v[0:3]
	v_mfma_f32_16x16x32_bf16 v[4:7], v[80:83], v[116:119], v[4:7]
	v_mfma_f32_16x16x32_bf16 v[8:11], v[80:83], v[120:123], v[8:11]
	v_mfma_f32_16x16x32_bf16 v[12:15], v[80:83], v[124:127], v[12:15]
	s_waitcnt lgkmcnt(2)
	v_mfma_f32_16x16x32_bf16 v[16:19], v[84:87], v[112:115], v[16:19]
	v_mfma_f32_16x16x32_bf16 v[20:23], v[84:87], v[116:119], v[20:23]
	v_mfma_f32_16x16x32_bf16 v[24:27], v[84:87], v[120:123], v[24:27]
	v_mfma_f32_16x16x32_bf16 v[28:31], v[84:87], v[124:127], v[28:31]
	s_waitcnt lgkmcnt(1)
	v_mfma_f32_16x16x32_bf16 v[32:35], v[88:91], v[112:115], v[32:35]
	v_mfma_f32_16x16x32_bf16 v[36:39], v[88:91], v[116:119], v[36:39]
	v_mfma_f32_16x16x32_bf16 v[40:43], v[88:91], v[120:123], v[40:43]
	v_mfma_f32_16x16x32_bf16 v[44:47], v[88:91], v[124:127], v[44:47]
	s_waitcnt lgkmcnt(0)
	v_mfma_f32_16x16x32_bf16 v[48:51], v[92:95], v[112:115], v[48:51]
	v_mfma_f32_16x16x32_bf16 v[52:55], v[92:95], v[116:119], v[52:55]
	v_mfma_f32_16x16x32_bf16 v[56:59], v[92:95], v[120:123], v[56:59]
	v_mfma_f32_16x16x32_bf16 v[60:63], v[92:95], v[124:127], v[60:63]
	s_waitcnt vmcnt(0)
	s_barrier
	ds_read_b128 v[64:67], v138 offset:0
	ds_read_b128 v[96:99], v142 offset:0
	ds_read_b128 v[100:103], v142 offset:2048
	ds_read_b128 v[104:107], v142 offset:4096
	ds_read_b128 v[108:111], v142 offset:6144
	ds_read_b128 v[68:71], v138 offset:2048
	ds_read_b128 v[72:75], v138 offset:4096
	ds_read_b128 v[76:79], v138 offset:6144
	s_waitcnt lgkmcnt(3)
	v_mfma_f32_16x16x32_bf16 v[0:3], v[64:67], v[96:99], v[0:3]
	v_mfma_f32_16x16x32_bf16 v[4:7], v[64:67], v[100:103], v[4:7]
	ds_read_b128 v[80:83], v139 offset:0
	v_mfma_f32_16x16x32_bf16 v[8:11], v[64:67], v[104:107], v[8:11]
	v_mfma_f32_16x16x32_bf16 v[12:15], v[64:67], v[108:111], v[12:15]
	ds_read_b128 v[112:115], v143 offset:0
	s_waitcnt lgkmcnt(4)
	v_mfma_f32_16x16x32_bf16 v[16:19], v[68:71], v[96:99], v[16:19]
	v_mfma_f32_16x16x32_bf16 v[20:23], v[68:71], v[100:103], v[20:23]
	ds_read_b128 v[116:119], v143 offset:2048
	v_mfma_f32_16x16x32_bf16 v[24:27], v[68:71], v[104:107], v[24:27]
	v_mfma_f32_16x16x32_bf16 v[28:31], v[68:71], v[108:111], v[28:31]
	ds_read_b128 v[120:123], v143 offset:4096
	s_waitcnt lgkmcnt(5)
	v_mfma_f32_16x16x32_bf16 v[32:35], v[72:75], v[96:99], v[32:35]
	v_mfma_f32_16x16x32_bf16 v[36:39], v[72:75], v[100:103], v[36:39]
	ds_read_b128 v[124:127], v143 offset:6144
	v_mfma_f32_16x16x32_bf16 v[40:43], v[72:75], v[104:107], v[40:43]
	v_mfma_f32_16x16x32_bf16 v[44:47], v[72:75], v[108:111], v[44:47]
	ds_read_b128 v[84:87], v139 offset:2048
	s_waitcnt lgkmcnt(6)
	v_mfma_f32_16x16x32_bf16 v[48:51], v[76:79], v[96:99], v[48:51]
	v_mfma_f32_16x16x32_bf16 v[52:55], v[76:79], v[100:103], v[52:55]
	ds_read_b128 v[88:91], v139 offset:4096
	v_mfma_f32_16x16x32_bf16 v[56:59], v[76:79], v[104:107], v[56:59]
	v_mfma_f32_16x16x32_bf16 v[60:63], v[76:79], v[108:111], v[60:63]
	ds_read_b128 v[92:95], v139 offset:6144
	s_waitcnt lgkmcnt(3)
	v_mfma_f32_16x16x32_bf16 v[0:3], v[80:83], v[112:115], v[0:3]
	v_mfma_f32_16x16x32_bf16 v[4:7], v[80:83], v[116:119], v[4:7]
	v_mfma_f32_16x16x32_bf16 v[8:11], v[80:83], v[120:123], v[8:11]
	v_mfma_f32_16x16x32_bf16 v[12:15], v[80:83], v[124:127], v[12:15]
	s_waitcnt lgkmcnt(2)
	v_mfma_f32_16x16x32_bf16 v[16:19], v[84:87], v[112:115], v[16:19]
	v_mfma_f32_16x16x32_bf16 v[20:23], v[84:87], v[116:119], v[20:23]
	v_mfma_f32_16x16x32_bf16 v[24:27], v[84:87], v[120:123], v[24:27]
	v_mfma_f32_16x16x32_bf16 v[28:31], v[84:87], v[124:127], v[28:31]
	s_waitcnt lgkmcnt(1)
	v_mfma_f32_16x16x32_bf16 v[32:35], v[88:91], v[112:115], v[32:35]
	v_mfma_f32_16x16x32_bf16 v[36:39], v[88:91], v[116:119], v[36:39]
	v_mfma_f32_16x16x32_bf16 v[40:43], v[88:91], v[120:123], v[40:43]
	v_mfma_f32_16x16x32_bf16 v[44:47], v[88:91], v[124:127], v[44:47]
	s_waitcnt lgkmcnt(0)
	v_mfma_f32_16x16x32_bf16 v[48:51], v[92:95], v[112:115], v[48:51]
	v_mfma_f32_16x16x32_bf16 v[52:55], v[92:95], v[116:119], v[52:55]
	v_mfma_f32_16x16x32_bf16 v[56:59], v[92:95], v[120:123], v[56:59]
	v_mfma_f32_16x16x32_bf16 v[60:63], v[92:95], v[124:127], v[60:63]
	s_add_i32 s100, s100, 1
	s_cmp_lt_u32 s100, 9
	s_cbranch_scc0 .Lgin_r9
	s_and_b32 s0, s101, 7
	s_add_i32 s0, s0, s100
	s_cmp_ge_u32 s0, 9
	s_cbranch_scc0 .Lgin_rk
	s_sub_u32 s0, s0, 9
.Lgin_rk:
	s_lshl_b32 s0, s0, 9
	s_add_i32 s38, s0, s101
	s_branch .Lgin_have
.Lgin_r9:
	s_cmp_eq_u32 s100, 9
	s_cbranch_scc0 .Lgin_none
	s_add_i32 s38, s101, 0x1200
	s_branch .Lgin_have
.Lgin_none:
	s_movk_i32 s38, 0x7fff
.Lgin_have:
	s_cmpk_lt_u32 s38, 0x1280
	s_cbranch_scc0 .Lgin_nonext
	s_and_b32 s0, s38, 63
	s_lshr_b32 s1, s38, 6
	s_mul_i32 s4, s70, 0x1280000
	s_lshl_b32 s39, s1, 18
	s_add_u32 s4, s4, s39
	s_add_u32 s26, s96, s4
	s_addc_u32 s27, s97, 0
	s_lshl_b32 s4, s0, 18
	s_add_u32 s4, s4, 0x82a6100
	s_add_u32 s28, s96, s4
	s_addc_u32 s29, s97, 0
	s_lshl_b32 s0, s98, 7
	s_add_u32 s26, s26, s0
	s_addc_u32 s27, s27, 0
	s_add_u32 s28, s28, s0
	s_addc_u32 s29, s29, 0
	s_mov_b32 s99, s98
	s_mov_b32 m0, s5
	s_nop 0
	global_load_lds_dwordx4 v132, s[26:27] offset:0
	global_load_lds_dwordx4 v133, s[26:27] offset:1024
	global_load_lds_dwordx4 v134, s[26:27] offset:2048
	global_load_lds_dwordx4 v135, s[26:27] offset:3072
	s_mov_b32 m0, s6
	s_nop 0
	global_load_lds_dwordx4 v132, s[28:29] offset:0
	global_load_lds_dwordx4 v133, s[28:29] offset:1024
	global_load_lds_dwordx4 v134, s[28:29] offset:2048
	global_load_lds_dwordx4 v135, s[28:29] offset:3072
